# G1 SwiGLU epilogue regenerated: staged/interleaved with packed f32 ops and saddr stores (311 vs 632 lines)
# speedup vs baseline: 1.0010x; 1.0010x over previous
.LBB0_123:
	v_lshl_add_u32 v140, s65, 8, v142
	v_lshl_or_b32 v141, s64, 7, v144
	v_mul_u32_u24_e32 v140, 0x1600, v140
	v_lshl_add_u32 v140, v141, 1, v140
	s_mov_b64 s[50:51], -1
	s_andn2_b64 vcc, exec, s[38:39]
	s_mov_b32 s10, 0xbfb8aa3b
	v_pk_mul_f32 v[146:147], v[126:127], s[10:11] op_sel_hi:[1,0]
	v_pk_mul_f32 v[148:149], v[128:129], s[10:11] op_sel_hi:[1,0]
	v_pk_mul_f32 v[150:151], v[118:119], s[10:11] op_sel_hi:[1,0]
	v_pk_mul_f32 v[152:153], v[120:121], s[10:11] op_sel_hi:[1,0]
	v_pk_mul_f32 v[154:155], v[110:111], s[10:11] op_sel_hi:[1,0]
	v_pk_mul_f32 v[156:157], v[112:113], s[10:11] op_sel_hi:[1,0]
	v_pk_mul_f32 v[158:159], v[102:103], s[10:11] op_sel_hi:[1,0]
	v_pk_mul_f32 v[160:161], v[104:105], s[10:11] op_sel_hi:[1,0]
	v_exp_f32_e32 v146, v146
	v_exp_f32_e32 v147, v147
	v_exp_f32_e32 v148, v148
	v_exp_f32_e32 v149, v149
	v_exp_f32_e32 v150, v150
	v_exp_f32_e32 v151, v151
	v_exp_f32_e32 v152, v152
	v_exp_f32_e32 v153, v153
	v_exp_f32_e32 v154, v154
	v_exp_f32_e32 v155, v155
	v_exp_f32_e32 v156, v156
	v_exp_f32_e32 v157, v157
	v_exp_f32_e32 v158, v158
	v_exp_f32_e32 v159, v159
	v_exp_f32_e32 v160, v160
	v_exp_f32_e32 v161, v161
	v_pk_add_f32 v[146:147], v[146:147], 1.0 op_sel_hi:[1,0]
	v_pk_add_f32 v[148:149], v[148:149], 1.0 op_sel_hi:[1,0]
	v_pk_add_f32 v[150:151], v[150:151], 1.0 op_sel_hi:[1,0]
	v_pk_add_f32 v[152:153], v[152:153], 1.0 op_sel_hi:[1,0]
	v_pk_add_f32 v[154:155], v[154:155], 1.0 op_sel_hi:[1,0]
	v_pk_add_f32 v[156:157], v[156:157], 1.0 op_sel_hi:[1,0]
	v_pk_add_f32 v[158:159], v[158:159], 1.0 op_sel_hi:[1,0]
	v_pk_add_f32 v[160:161], v[160:161], 1.0 op_sel_hi:[1,0]
	v_rcp_f32_e32 v146, v146
	v_rcp_f32_e32 v147, v147
	v_rcp_f32_e32 v148, v148
	v_rcp_f32_e32 v149, v149
	v_rcp_f32_e32 v150, v150
	v_rcp_f32_e32 v151, v151
	v_rcp_f32_e32 v152, v152
	v_rcp_f32_e32 v153, v153
	v_rcp_f32_e32 v154, v154
	v_rcp_f32_e32 v155, v155
	v_rcp_f32_e32 v156, v156
	v_rcp_f32_e32 v157, v157
	v_rcp_f32_e32 v158, v158
	v_rcp_f32_e32 v159, v159
	v_rcp_f32_e32 v160, v160
	v_rcp_f32_e32 v161, v161
	v_pk_mul_f32 v[126:127], v[126:127], v[146:147]
	v_pk_mul_f32 v[128:129], v[128:129], v[148:149]
	v_pk_mul_f32 v[118:119], v[118:119], v[150:151]
	v_pk_mul_f32 v[120:121], v[120:121], v[152:153]
	v_pk_mul_f32 v[110:111], v[110:111], v[154:155]
	v_pk_mul_f32 v[112:113], v[112:113], v[156:157]
	v_pk_mul_f32 v[102:103], v[102:103], v[158:159]
	v_pk_mul_f32 v[104:105], v[104:105], v[160:161]
	v_pk_mul_f32 v[126:127], v[126:127], v[122:123]
	v_pk_mul_f32 v[128:129], v[128:129], v[124:125]
	v_pk_mul_f32 v[118:119], v[118:119], v[114:115]
	v_pk_mul_f32 v[120:121], v[120:121], v[116:117]
	v_pk_mul_f32 v[110:111], v[110:111], v[106:107]
	v_pk_mul_f32 v[112:113], v[112:113], v[108:109]
	v_pk_mul_f32 v[102:103], v[102:103], v[98:99]
	v_pk_mul_f32 v[104:105], v[104:105], v[100:101]
	v_cvt_pk_bf16_f32 v162, v126, v127
	v_cvt_pk_bf16_f32 v163, v128, v129
	v_cvt_pk_bf16_f32 v164, v118, v119
	v_cvt_pk_bf16_f32 v165, v120, v121
	v_cvt_pk_bf16_f32 v166, v110, v111
	v_cvt_pk_bf16_f32 v167, v112, v113
	v_cvt_pk_bf16_f32 v168, v102, v103
	v_cvt_pk_bf16_f32 v169, v104, v105
	v_mov_b32_e32 v141, v140
	global_store_dwordx4 v141, v[162:165], s[80:81]
	v_add_u32_e32 v141, 0x16000, v140
	global_store_dwordx4 v141, v[166:169], s[80:81]
	v_pk_mul_f32 v[146:147], v[94:95], s[10:11] op_sel_hi:[1,0]
	v_pk_mul_f32 v[148:149], v[96:97], s[10:11] op_sel_hi:[1,0]
	v_pk_mul_f32 v[150:151], v[86:87], s[10:11] op_sel_hi:[1,0]
	v_pk_mul_f32 v[152:153], v[88:89], s[10:11] op_sel_hi:[1,0]
	v_pk_mul_f32 v[154:155], v[78:79], s[10:11] op_sel_hi:[1,0]
	v_pk_mul_f32 v[156:157], v[80:81], s[10:11] op_sel_hi:[1,0]
	v_pk_mul_f32 v[158:159], v[70:71], s[10:11] op_sel_hi:[1,0]
	v_pk_mul_f32 v[160:161], v[72:73], s[10:11] op_sel_hi:[1,0]
	v_exp_f32_e32 v146, v146
	v_exp_f32_e32 v147, v147
	v_exp_f32_e32 v148, v148
	v_exp_f32_e32 v149, v149
	v_exp_f32_e32 v150, v150
	v_exp_f32_e32 v151, v151
	v_exp_f32_e32 v152, v152
	v_exp_f32_e32 v153, v153
	v_exp_f32_e32 v154, v154
	v_exp_f32_e32 v155, v155
	v_exp_f32_e32 v156, v156
	v_exp_f32_e32 v157, v157
	v_exp_f32_e32 v158, v158
	v_exp_f32_e32 v159, v159
	v_exp_f32_e32 v160, v160
	v_exp_f32_e32 v161, v161
	v_pk_add_f32 v[146:147], v[146:147], 1.0 op_sel_hi:[1,0]
	v_pk_add_f32 v[148:149], v[148:149], 1.0 op_sel_hi:[1,0]
	v_pk_add_f32 v[150:151], v[150:151], 1.0 op_sel_hi:[1,0]
	v_pk_add_f32 v[152:153], v[152:153], 1.0 op_sel_hi:[1,0]
	v_pk_add_f32 v[154:155], v[154:155], 1.0 op_sel_hi:[1,0]
	v_pk_add_f32 v[156:157], v[156:157], 1.0 op_sel_hi:[1,0]
	v_pk_add_f32 v[158:159], v[158:159], 1.0 op_sel_hi:[1,0]
	v_pk_add_f32 v[160:161], v[160:161], 1.0 op_sel_hi:[1,0]
	v_rcp_f32_e32 v146, v146
	v_rcp_f32_e32 v147, v147
	v_rcp_f32_e32 v148, v148
	v_rcp_f32_e32 v149, v149
	v_rcp_f32_e32 v150, v150
	v_rcp_f32_e32 v151, v151
	v_rcp_f32_e32 v152, v152
	v_rcp_f32_e32 v153, v153
	v_rcp_f32_e32 v154, v154
	v_rcp_f32_e32 v155, v155
	v_rcp_f32_e32 v156, v156
	v_rcp_f32_e32 v157, v157
	v_rcp_f32_e32 v158, v158
	v_rcp_f32_e32 v159, v159
	v_rcp_f32_e32 v160, v160
	v_rcp_f32_e32 v161, v161
	v_pk_mul_f32 v[94:95], v[94:95], v[146:147]
	v_pk_mul_f32 v[96:97], v[96:97], v[148:149]
	v_pk_mul_f32 v[86:87], v[86:87], v[150:151]
	v_pk_mul_f32 v[88:89], v[88:89], v[152:153]
	v_pk_mul_f32 v[78:79], v[78:79], v[154:155]
	v_pk_mul_f32 v[80:81], v[80:81], v[156:157]
	v_pk_mul_f32 v[70:71], v[70:71], v[158:159]
	v_pk_mul_f32 v[72:73], v[72:73], v[160:161]
	v_pk_mul_f32 v[94:95], v[94:95], v[90:91]
	v_pk_mul_f32 v[96:97], v[96:97], v[92:93]
	v_pk_mul_f32 v[86:87], v[86:87], v[82:83]
	v_pk_mul_f32 v[88:89], v[88:89], v[84:85]
	v_pk_mul_f32 v[78:79], v[78:79], v[74:75]
	v_pk_mul_f32 v[80:81], v[80:81], v[76:77]
	v_pk_mul_f32 v[70:71], v[70:71], v[66:67]
	v_pk_mul_f32 v[72:73], v[72:73], v[68:69]
	v_cvt_pk_bf16_f32 v162, v94, v95
	v_cvt_pk_bf16_f32 v163, v96, v97
	v_cvt_pk_bf16_f32 v164, v86, v87
	v_cvt_pk_bf16_f32 v165, v88, v89
	v_cvt_pk_bf16_f32 v166, v78, v79
	v_cvt_pk_bf16_f32 v167, v80, v81
	v_cvt_pk_bf16_f32 v168, v70, v71
	v_cvt_pk_bf16_f32 v169, v72, v73
	v_add_u32_e32 v141, 0x2c000, v140
	global_store_dwordx4 v141, v[162:165], s[80:81]
	v_add_u32_e32 v141, 0x42000, v140
	global_store_dwordx4 v141, v[166:169], s[80:81]
	v_pk_mul_f32 v[146:147], v[62:63], s[10:11] op_sel_hi:[1,0]
	v_pk_mul_f32 v[148:149], v[64:65], s[10:11] op_sel_hi:[1,0]
	v_pk_mul_f32 v[150:151], v[54:55], s[10:11] op_sel_hi:[1,0]
	v_pk_mul_f32 v[152:153], v[56:57], s[10:11] op_sel_hi:[1,0]
	v_pk_mul_f32 v[154:155], v[46:47], s[10:11] op_sel_hi:[1,0]
	v_pk_mul_f32 v[156:157], v[48:49], s[10:11] op_sel_hi:[1,0]
	v_pk_mul_f32 v[158:159], v[38:39], s[10:11] op_sel_hi:[1,0]
	v_pk_mul_f32 v[160:161], v[40:41], s[10:11] op_sel_hi:[1,0]
	v_exp_f32_e32 v146, v146
	v_exp_f32_e32 v147, v147
	v_exp_f32_e32 v148, v148
	v_exp_f32_e32 v149, v149
	v_exp_f32_e32 v150, v150
	v_exp_f32_e32 v151, v151
	v_exp_f32_e32 v152, v152
	v_exp_f32_e32 v153, v153
	v_exp_f32_e32 v154, v154
	v_exp_f32_e32 v155, v155
	v_exp_f32_e32 v156, v156
	v_exp_f32_e32 v157, v157
	v_exp_f32_e32 v158, v158
	v_exp_f32_e32 v159, v159
	v_exp_f32_e32 v160, v160
	v_exp_f32_e32 v161, v161
	v_pk_add_f32 v[146:147], v[146:147], 1.0 op_sel_hi:[1,0]
	v_pk_add_f32 v[148:149], v[148:149], 1.0 op_sel_hi:[1,0]
	v_pk_add_f32 v[150:151], v[150:151], 1.0 op_sel_hi:[1,0]
	v_pk_add_f32 v[152:153], v[152:153], 1.0 op_sel_hi:[1,0]
	v_pk_add_f32 v[154:155], v[154:155], 1.0 op_sel_hi:[1,0]
	v_pk_add_f32 v[156:157], v[156:157], 1.0 op_sel_hi:[1,0]
	v_pk_add_f32 v[158:159], v[158:159], 1.0 op_sel_hi:[1,0]
	v_pk_add_f32 v[160:161], v[160:161], 1.0 op_sel_hi:[1,0]
	v_rcp_f32_e32 v146, v146
	v_rcp_f32_e32 v147, v147
	v_rcp_f32_e32 v148, v148
	v_rcp_f32_e32 v149, v149
	v_rcp_f32_e32 v150, v150
	v_rcp_f32_e32 v151, v151
	v_rcp_f32_e32 v152, v152
	v_rcp_f32_e32 v153, v153
	v_rcp_f32_e32 v154, v154
	v_rcp_f32_e32 v155, v155
	v_rcp_f32_e32 v156, v156
	v_rcp_f32_e32 v157, v157
	v_rcp_f32_e32 v158, v158
	v_rcp_f32_e32 v159, v159
	v_rcp_f32_e32 v160, v160
	v_rcp_f32_e32 v161, v161
	v_pk_mul_f32 v[62:63], v[62:63], v[146:147]
	v_pk_mul_f32 v[64:65], v[64:65], v[148:149]
	v_pk_mul_f32 v[54:55], v[54:55], v[150:151]
	v_pk_mul_f32 v[56:57], v[56:57], v[152:153]
	v_pk_mul_f32 v[46:47], v[46:47], v[154:155]
	v_pk_mul_f32 v[48:49], v[48:49], v[156:157]
	v_pk_mul_f32 v[38:39], v[38:39], v[158:159]
	v_pk_mul_f32 v[40:41], v[40:41], v[160:161]
	v_pk_mul_f32 v[62:63], v[62:63], v[58:59]
	v_pk_mul_f32 v[64:65], v[64:65], v[60:61]
	v_pk_mul_f32 v[54:55], v[54:55], v[50:51]
	v_pk_mul_f32 v[56:57], v[56:57], v[52:53]
	v_pk_mul_f32 v[46:47], v[46:47], v[42:43]
	v_pk_mul_f32 v[48:49], v[48:49], v[44:45]
	v_pk_mul_f32 v[38:39], v[38:39], v[34:35]
	v_pk_mul_f32 v[40:41], v[40:41], v[36:37]
	v_cvt_pk_bf16_f32 v162, v62, v63
	v_cvt_pk_bf16_f32 v163, v64, v65
	v_cvt_pk_bf16_f32 v164, v54, v55
	v_cvt_pk_bf16_f32 v165, v56, v57
	v_cvt_pk_bf16_f32 v166, v46, v47
	v_cvt_pk_bf16_f32 v167, v48, v49
	v_cvt_pk_bf16_f32 v168, v38, v39
	v_cvt_pk_bf16_f32 v169, v40, v41
	v_add_u32_e32 v141, 0xb0000, v140
	global_store_dwordx4 v141, v[162:165], s[80:81]
	v_add_u32_e32 v141, 0xc6000, v140
	global_store_dwordx4 v141, v[166:169], s[80:81]
	v_pk_mul_f32 v[146:147], v[30:31], s[10:11] op_sel_hi:[1,0]
	v_pk_mul_f32 v[148:149], v[32:33], s[10:11] op_sel_hi:[1,0]
	v_pk_mul_f32 v[150:151], v[22:23], s[10:11] op_sel_hi:[1,0]
	v_pk_mul_f32 v[152:153], v[24:25], s[10:11] op_sel_hi:[1,0]
	v_pk_mul_f32 v[154:155], v[14:15], s[10:11] op_sel_hi:[1,0]
	v_pk_mul_f32 v[156:157], v[16:17], s[10:11] op_sel_hi:[1,0]
	v_pk_mul_f32 v[158:159], v[6:7], s[10:11] op_sel_hi:[1,0]
	v_pk_mul_f32 v[160:161], v[8:9], s[10:11] op_sel_hi:[1,0]
	v_exp_f32_e32 v146, v146
	v_exp_f32_e32 v147, v147
	v_exp_f32_e32 v148, v148
	v_exp_f32_e32 v149, v149
	v_exp_f32_e32 v150, v150
	v_exp_f32_e32 v151, v151
	v_exp_f32_e32 v152, v152
	v_exp_f32_e32 v153, v153
	v_exp_f32_e32 v154, v154
	v_exp_f32_e32 v155, v155
	v_exp_f32_e32 v156, v156
	v_exp_f32_e32 v157, v157
	v_exp_f32_e32 v158, v158
	v_exp_f32_e32 v159, v159
	v_exp_f32_e32 v160, v160
	v_exp_f32_e32 v161, v161
	v_pk_add_f32 v[146:147], v[146:147], 1.0 op_sel_hi:[1,0]
	v_pk_add_f32 v[148:149], v[148:149], 1.0 op_sel_hi:[1,0]
	v_pk_add_f32 v[150:151], v[150:151], 1.0 op_sel_hi:[1,0]
	v_pk_add_f32 v[152:153], v[152:153], 1.0 op_sel_hi:[1,0]
	v_pk_add_f32 v[154:155], v[154:155], 1.0 op_sel_hi:[1,0]
	v_pk_add_f32 v[156:157], v[156:157], 1.0 op_sel_hi:[1,0]
	v_pk_add_f32 v[158:159], v[158:159], 1.0 op_sel_hi:[1,0]
	v_pk_add_f32 v[160:161], v[160:161], 1.0 op_sel_hi:[1,0]
	v_rcp_f32_e32 v146, v146
	v_rcp_f32_e32 v147, v147
	v_rcp_f32_e32 v148, v148
	v_rcp_f32_e32 v149, v149
	v_rcp_f32_e32 v150, v150
	v_rcp_f32_e32 v151, v151
	v_rcp_f32_e32 v152, v152
	v_rcp_f32_e32 v153, v153
	v_rcp_f32_e32 v154, v154
	v_rcp_f32_e32 v155, v155
	v_rcp_f32_e32 v156, v156
	v_rcp_f32_e32 v157, v157
	v_rcp_f32_e32 v158, v158
	v_rcp_f32_e32 v159, v159
	v_rcp_f32_e32 v160, v160
	v_rcp_f32_e32 v161, v161
	v_pk_mul_f32 v[30:31], v[30:31], v[146:147]
	v_pk_mul_f32 v[32:33], v[32:33], v[148:149]
	v_pk_mul_f32 v[22:23], v[22:23], v[150:151]
	v_pk_mul_f32 v[24:25], v[24:25], v[152:153]
	v_pk_mul_f32 v[14:15], v[14:15], v[154:155]
	v_pk_mul_f32 v[16:17], v[16:17], v[156:157]
	v_pk_mul_f32 v[6:7], v[6:7], v[158:159]
	v_pk_mul_f32 v[8:9], v[8:9], v[160:161]
	v_pk_mul_f32 v[30:31], v[30:31], v[26:27]
	v_pk_mul_f32 v[32:33], v[32:33], v[28:29]
	v_pk_mul_f32 v[22:23], v[22:23], v[18:19]
	v_pk_mul_f32 v[24:25], v[24:25], v[20:21]
	v_pk_mul_f32 v[14:15], v[14:15], v[10:11]
	v_pk_mul_f32 v[16:17], v[16:17], v[12:13]
	v_pk_mul_f32 v[6:7], v[6:7], v[2:3]
	v_pk_mul_f32 v[8:9], v[8:9], v[4:5]
	v_cvt_pk_bf16_f32 v162, v30, v31
	v_cvt_pk_bf16_f32 v163, v32, v33
	v_cvt_pk_bf16_f32 v164, v22, v23
	v_cvt_pk_bf16_f32 v165, v24, v25
	v_cvt_pk_bf16_f32 v166, v14, v15
	v_cvt_pk_bf16_f32 v167, v16, v17
	v_cvt_pk_bf16_f32 v168, v6, v7
	v_cvt_pk_bf16_f32 v169, v8, v9
	v_add_u32_e32 v141, 0xdc000, v140
	global_store_dwordx4 v141, v[162:165], s[80:81]
	v_add_u32_e32 v141, 0xf2000, v140
	global_store_dwordx4 v141, v[166:169], s[80:81]
	s_cbranch_vccnz .LBB0_112
	s_andn2_b64 vcc, exec, s[0:1]
	s_cbranch_vccnz .LBB0_111
	s_barrier
	s_branch .LBB0_111
